# attention: staging moved to each kind after its address code; next item's prefetch issued before the staging barrier
# speedup vs baseline: 1.0037x; 1.0037x over previous
.LBB0_1272:
	s_and_b32 s8, s2, 2
	v_readlane_b32 s9, v252, 56
	s_or_b32 s74, s8, s9
	v_mov_b32_e32 v99, v218
	s_lshl_b32 s8, s74, 7
	v_readlane_b32 s9, v252, 55
	s_or_b32 s8, s9, s8
	v_readfirstlane_b32 s76, v99
	v_readlane_b32 s9, v253, 22
	s_ashr_i32 s73, s76, 6
	s_or_b32 s75, s8, s9
	v_and_b32_e32 v98, 63, v99
	s_cmp_gt_u32 s72, 1
	s_mov_b64 s[10:11], -1
	s_cbranch_scc0 .LBB0_1352
	s_cmp_gt_u32 s72, 3
	s_cbranch_scc0 .LBB0_1314
	s_lshl_b32 s77, s75, 7
	s_and_b32 s12, s77, 0x180
	v_ashrrev_i32_e32 v104, 4, v99
	s_movk_i32 s9, 0x120
	s_cmp_gt_u32 s72, 5
	v_mul_lo_u32 v102, v104, s33
	v_mul_lo_u32 v103, v104, s9
	s_cbranch_scc0 .LBB0_1276
	s_lshl_b32 s10, s8, 5
	s_lshl_b32 s28, s12, 1
	s_add_u32 s8, s66, s28
	v_lshl_add_u32 v0, s74, 8, v104
	v_lshlrev_b32_e32 v1, 4, v99
	s_addc_u32 s9, s67, 0
	v_and_b32_e32 v32, 0xf0, v1
	v_ashrrev_i32_e32 v1, 31, v0
	v_lshl_add_u64 v[2:3], s[8:9], 0, v[32:33]
	v_lshlrev_b64 v[0:1], 13, v[0:1]
	v_lshl_add_u64 v[0:1], v[2:3], 0, v[0:1]
	s_mov_b64 s[8:9], 0x40000
	v_lshl_add_u64 v[2:3], v[0:1], 0, s[8:9]
	s_mov_b32 s8, 0x40000
	v_add_co_u32_e32 v12, vcc, s8, v0
	s_mov_b64 s[8:9], 0x80000
	s_nop 0
	v_addc_co_u32_e32 v13, vcc, 0, v1, vcc
	s_nop 0
	s_nop 0
	v_lshl_add_u64 v[2:3], v[0:1], 0, s[8:9]
	s_mov_b32 s8, 0x80000
	v_add_co_u32_e32 v20, vcc, s8, v0
	s_mov_b64 s[8:9], 0xc0000
	s_nop 0
	v_addc_co_u32_e32 v21, vcc, 0, v1, vcc
	s_nop 0
	v_lshl_add_u64 v[2:3], v[0:1], 0, s[8:9]
	s_mov_b32 s8, 0xc0000
	v_add_co_u32_e32 v28, vcc, s8, v0
	s_mov_b64 s[8:9], 0x100000
	s_nop 0
	v_addc_co_u32_e32 v29, vcc, 0, v1, vcc
	v_add_co_u32_e32 v38, vcc, s79, v0
	s_nop 0
	v_lshl_add_u64 v[2:3], v[0:1], 0, s[8:9]
	v_addc_co_u32_e32 v39, vcc, 0, v1, vcc
	s_mov_b64 s[8:9], 0x140000
	s_nop 0
	v_lshl_add_u64 v[2:3], v[0:1], 0, s[8:9]
	s_mov_b32 s8, 0x140000
	v_add_co_u32_e32 v46, vcc, s8, v0
	s_mov_b64 s[8:9], 0x180000
	s_nop 0
	v_addc_co_u32_e32 v47, vcc, 0, v1, vcc
	s_nop 0
	v_lshl_add_u64 v[2:3], v[0:1], 0, s[8:9]
	s_mov_b32 s8, 0x180000
	v_add_co_u32_e32 v54, vcc, s8, v0
	s_mov_b64 s[8:9], 0x1c0000
	s_nop 0
	v_addc_co_u32_e32 v55, vcc, 0, v1, vcc
	s_nop 0
	v_lshl_add_u64 v[2:3], v[0:1], 0, s[8:9]
	s_mov_b32 s8, 0x1c0000
	v_add_co_u32_e32 v0, vcc, s8, v0
	s_and_b32 s10, s10, 0x3f80
	s_nop 0
	v_addc_co_u32_e32 v1, vcc, 0, v1, vcc
	v_readlane_b32 s8, v252, 31
	s_add_u32 s8, s8, s28
	v_readlane_b32 s9, v252, 32
	s_addc_u32 s9, s9, 0
	s_lshl_b32 s11, s73, 4
	v_and_b32_e32 v108, 15, v99
	s_add_i32 s11, s11, s10
	v_or_b32_e32 v82, s11, v108
	v_mov_b64_e32 v[0:1], s[8:9]
	v_mad_i64_i32 v[0:1], s[8:9], v82, s70, v[0:1]
	v_and_b32_e32 v106, 48, v99
	v_mov_b32_e32 v107, v33
	v_lshl_add_u64 v[70:71], v[0:1], 0, v[106:107]
	v_add3_u32 v83, 0, v32, v102
	s_nop 0
	v_lshrrev_b32_e32 v105, 2, v98
	v_add3_u32 v4, s27, v32, v103
	v_lshrrev_b32_e32 v6, 1, v98
	v_and_b32_e32 v32, 24, v6
	v_mov_b64_e32 v[4:5], s[24:25]
	v_mad_i64_i32 v[4:5], s[8:9], v82, s70, v[4:5]
	v_lshl_add_u64 v[4:5], v[4:5], 0, s[28:29]
	v_lshl_add_u64 v[4:5], v[4:5], 0, v[32:33]
	s_mov_b64 s[8:9], 0x11103000
	v_lshl_add_u64 v[78:79], v[4:5], 0, s[8:9]
	s_mov_b32 s8, 0x11103000
	v_add_co_u32_e32 v94, vcc, s8, v4
	s_waitcnt lgkmcnt(0)
	s_nop 0
	v_addc_co_u32_e32 v95, vcc, 0, v5, vcc
	v_lshrrev_b32_e32 v227, 4, v218
	v_and_b32_e32 v244, 15, v218
	v_lshlrev_b32_e32 v244, 4, v244
	v_mul_u32_u24_e32 v245, 0x120, v227
	v_add3_u32 v245, s27, v244, v245
	v_mad_u32_u24 v244, v227, s33, v244
	s_cmp_lg_u32 s72, 0
	s_cbranch_scc1 .Lpf_wait_cnt3
	s_waitcnt vmcnt(0)
.Lpf_wait_cnt3:
	s_waitcnt vmcnt(8)
	ds_write_b128 v244, v[154:157]
	ds_write_b128 v245, v[158:161]
	ds_write_b128 v244, v[162:165] offset:8704
	ds_write_b128 v245, v[166:169] offset:9216
	ds_write_b128 v244, v[170:173] offset:17408
	ds_write_b128 v245, v[174:177] offset:18432
	ds_write_b128 v244, v[178:181] offset:26112
	ds_write_b128 v245, v[182:185] offset:27648
	ds_write_b128 v244, v[186:189] offset:34816
	ds_write_b128 v245, v[190:193] offset:36864
	ds_write_b128 v244, v[194:197] offset:43520
	ds_write_b128 v245, v[198:201] offset:46080
	ds_write_b128 v244, v[202:205] offset:52224
	ds_write_b128 v245, v[206:209] offset:55296
	ds_write_b128 v244, v[210:213] offset:60928
	ds_write_b128 v245, v[214:217] offset:64512
	v_mov_b64_e32 v[0:1], v[228:229]
	v_mov_b64_e32 v[2:3], v[230:231]
	v_mov_b64_e32 v[62:63], v[232:233]
	v_mov_b64_e32 v[64:65], v[234:235]
	v_mov_b64_e32 v[66:67], v[236:237]
	v_mov_b64_e32 v[68:69], v[238:239]
	v_mov_b64_e32 v[70:71], v[240:241]
	v_mov_b64_e32 v[72:73], v[242:243]
	s_add_u32 s48, s72, 1
	s_cmp_lt_u32 s48, 8
	s_cbranch_scc1 .Lpf_issue
.Lpf_ret_k3:
	s_waitcnt lgkmcnt(0)
	s_barrier
	global_load_dwordx2 v[96:97], v[94:95], off
	global_load_dwordx2 v[92:93], v[78:79], off offset:32
	global_load_dwordx2 v[90:91], v[78:79], off offset:64
	global_load_dwordx2 v[88:89], v[78:79], off offset:96
	global_load_dwordx2 v[86:87], v[78:79], off offset:128
	global_load_dwordx2 v[84:85], v[78:79], off offset:160
	global_load_dwordx2 v[82:83], v[78:79], off offset:192
	global_load_dwordx2 v[80:81], v[78:79], off offset:224
	v_add_u32_e32 v32, 0, v106
	v_mad_u32_u24 v126, v108, s33, v32
	ds_read_b128 v[4:7], v126
	ds_read_b128 v[8:11], v126 offset:64
	ds_read_b128 v[12:15], v126 offset:128
	ds_read_b128 v[16:19], v126 offset:192
	ds_read_b128 v[20:23], v126 offset:4352
	ds_read_b128 v[24:27], v126 offset:4416
	ds_read_b128 v[28:31], v126 offset:4480
	ds_read_b128 v[34:37], v126 offset:4544
	s_waitcnt lgkmcnt(7)
	v_mfma_f32_16x16x32_bf16 v[4:7], v[4:7], v[0:3], 0
	s_waitcnt lgkmcnt(6)
	v_mfma_f32_16x16x32_bf16 v[4:7], v[8:11], v[62:65], v[4:7]
	s_waitcnt lgkmcnt(5)
	v_mfma_f32_16x16x32_bf16 v[4:7], v[12:15], v[66:69], v[4:7]
	s_waitcnt lgkmcnt(4)
	v_mfma_f32_16x16x32_bf16 v[74:77], v[16:19], v[70:73], v[4:7]
	s_waitcnt lgkmcnt(3)
	v_mfma_f32_16x16x32_bf16 v[4:7], v[20:23], v[0:3], 0
	s_waitcnt lgkmcnt(2)
	v_mfma_f32_16x16x32_bf16 v[4:7], v[24:27], v[62:65], v[4:7]
	s_waitcnt lgkmcnt(1)
	v_mfma_f32_16x16x32_bf16 v[4:7], v[28:31], v[66:69], v[4:7]
	s_waitcnt lgkmcnt(0)
	v_mfma_f32_16x16x32_bf16 v[58:61], v[34:37], v[70:73], v[4:7]
	v_or_b32_e32 v20, 48, v98
	v_mad_u32_u24 v34, v20, s33, v32
	s_nop 3
	ds_read_b128 v[4:7], v126 offset:8704
	ds_read_b128 v[8:11], v126 offset:8768
	ds_read_b128 v[12:15], v126 offset:8832
	ds_read_b128 v[16:19], v126 offset:8896
	ds_read_b128 v[20:23], v34
	ds_read_b128 v[24:27], v34 offset:64
	ds_read_b128 v[28:31], v34 offset:128
	ds_read_b128 v[34:37], v34 offset:192
	s_waitcnt lgkmcnt(7)
	v_mfma_f32_16x16x32_bf16 v[4:7], v[4:7], v[0:3], 0
	s_waitcnt lgkmcnt(6)
	v_mfma_f32_16x16x32_bf16 v[4:7], v[8:11], v[62:65], v[4:7]
	s_waitcnt lgkmcnt(5)
	v_mfma_f32_16x16x32_bf16 v[4:7], v[12:15], v[66:69], v[4:7]
	s_waitcnt lgkmcnt(4)
	v_mfma_f32_16x16x32_bf16 v[54:57], v[16:19], v[70:73], v[4:7]
	s_waitcnt lgkmcnt(3)
	v_mfma_f32_16x16x32_bf16 v[4:7], v[20:23], v[0:3], 0
	s_waitcnt lgkmcnt(2)
	v_mfma_f32_16x16x32_bf16 v[4:7], v[24:27], v[62:65], v[4:7]
	s_waitcnt lgkmcnt(1)
	v_mfma_f32_16x16x32_bf16 v[4:7], v[28:31], v[66:69], v[4:7]
	s_waitcnt lgkmcnt(0)
	v_mfma_f32_16x16x32_bf16 v[50:53], v[34:37], v[70:73], v[4:7]
	s_nop 5
	ds_read_b128 v[4:7], v126 offset:17408
	ds_read_b128 v[8:11], v126 offset:17472
	ds_read_b128 v[12:15], v126 offset:17536
	ds_read_b128 v[16:19], v126 offset:17600
	ds_read_b128 v[20:23], v126 offset:21760
	ds_read_b128 v[24:27], v126 offset:21824
	ds_read_b128 v[28:31], v126 offset:21888
	ds_read_b128 v[34:37], v126 offset:21952
	s_waitcnt lgkmcnt(7)
	v_mfma_f32_16x16x32_bf16 v[4:7], v[4:7], v[0:3], 0
	s_waitcnt lgkmcnt(6)
	v_mfma_f32_16x16x32_bf16 v[4:7], v[8:11], v[62:65], v[4:7]
	s_waitcnt lgkmcnt(5)
	v_mfma_f32_16x16x32_bf16 v[4:7], v[12:15], v[66:69], v[4:7]
	s_waitcnt lgkmcnt(4)
	v_mfma_f32_16x16x32_bf16 v[46:49], v[16:19], v[70:73], v[4:7]
	s_waitcnt lgkmcnt(3)
	v_mfma_f32_16x16x32_bf16 v[4:7], v[20:23], v[0:3], 0
	s_waitcnt lgkmcnt(2)
	v_mfma_f32_16x16x32_bf16 v[4:7], v[24:27], v[62:65], v[4:7]
	s_waitcnt lgkmcnt(1)
	v_mfma_f32_16x16x32_bf16 v[4:7], v[28:31], v[66:69], v[4:7]
	s_waitcnt lgkmcnt(0)
	v_mfma_f32_16x16x32_bf16 v[42:45], v[34:37], v[70:73], v[4:7]
	v_or_b32_e32 v20, 0x70, v98
	v_mad_u32_u24 v34, v20, s33, v32
	s_nop 3
	ds_read_b128 v[4:7], v126 offset:26112
	ds_read_b128 v[8:11], v126 offset:26176
	ds_read_b128 v[12:15], v126 offset:26240
	ds_read_b128 v[16:19], v126 offset:26304
	ds_read_b128 v[20:23], v34
	ds_read_b128 v[24:27], v34 offset:64
	ds_read_b128 v[28:31], v34 offset:128
	ds_read_b128 v[34:37], v34 offset:192
	s_waitcnt lgkmcnt(7)
	v_mfma_f32_16x16x32_bf16 v[4:7], v[4:7], v[0:3], 0
	s_waitcnt lgkmcnt(6)
	v_mfma_f32_16x16x32_bf16 v[4:7], v[8:11], v[62:65], v[4:7]
	s_waitcnt lgkmcnt(5)
	v_mfma_f32_16x16x32_bf16 v[4:7], v[12:15], v[66:69], v[4:7]
	s_waitcnt lgkmcnt(4)
	v_mfma_f32_16x16x32_bf16 v[38:41], v[16:19], v[70:73], v[4:7]
	s_waitcnt lgkmcnt(3)
	v_mfma_f32_16x16x32_bf16 v[4:7], v[20:23], v[0:3], 0
	s_waitcnt lgkmcnt(2)
	v_mfma_f32_16x16x32_bf16 v[4:7], v[24:27], v[62:65], v[4:7]
	s_waitcnt lgkmcnt(1)
	v_mfma_f32_16x16x32_bf16 v[4:7], v[28:31], v[66:69], v[4:7]
	s_waitcnt lgkmcnt(0)
	v_mfma_f32_16x16x32_bf16 v[34:37], v[34:37], v[70:73], v[4:7]
	s_nop 5
	ds_read_b128 v[4:7], v126 offset:34816
	ds_read_b128 v[8:11], v126 offset:34880
	ds_read_b128 v[12:15], v126 offset:34944
	ds_read_b128 v[16:19], v126 offset:35008
	ds_read_b128 v[20:23], v126 offset:39168
	ds_read_b128 v[24:27], v126 offset:39232
	ds_read_b128 v[106:109], v126 offset:39296
	ds_read_b128 v[110:113], v126 offset:39360
	s_waitcnt lgkmcnt(7)
	v_mfma_f32_16x16x32_bf16 v[4:7], v[4:7], v[0:3], 0
	s_waitcnt lgkmcnt(6)
	v_mfma_f32_16x16x32_bf16 v[4:7], v[8:11], v[62:65], v[4:7]
	s_waitcnt lgkmcnt(5)
	v_mfma_f32_16x16x32_bf16 v[4:7], v[12:15], v[66:69], v[4:7]
	s_waitcnt lgkmcnt(4)
	v_mfma_f32_16x16x32_bf16 v[28:31], v[16:19], v[70:73], v[4:7]
	s_waitcnt lgkmcnt(3)
	v_mfma_f32_16x16x32_bf16 v[4:7], v[20:23], v[0:3], 0
	s_waitcnt lgkmcnt(2)
	v_mfma_f32_16x16x32_bf16 v[4:7], v[24:27], v[62:65], v[4:7]
	s_waitcnt lgkmcnt(1)
	v_mfma_f32_16x16x32_bf16 v[4:7], v[106:109], v[66:69], v[4:7]
	s_waitcnt lgkmcnt(0)
	v_mfma_f32_16x16x32_bf16 v[24:27], v[110:113], v[70:73], v[4:7]
	v_or_b32_e32 v20, 0xb0, v98
	v_mad_u32_u24 v20, v20, s33, v32
	s_nop 3
	ds_read_b128 v[4:7], v126 offset:43520
	ds_read_b128 v[8:11], v126 offset:43584
	ds_read_b128 v[12:15], v126 offset:43648
	ds_read_b128 v[16:19], v126 offset:43712
	ds_read_b128 v[106:109], v20
	ds_read_b128 v[110:113], v20 offset:64
	ds_read_b128 v[114:117], v20 offset:128
	ds_read_b128 v[118:121], v20 offset:192
	s_waitcnt lgkmcnt(7)
	v_mfma_f32_16x16x32_bf16 v[4:7], v[4:7], v[0:3], 0
	s_waitcnt lgkmcnt(6)
	v_mfma_f32_16x16x32_bf16 v[4:7], v[8:11], v[62:65], v[4:7]
	s_waitcnt lgkmcnt(5)
	v_mfma_f32_16x16x32_bf16 v[4:7], v[12:15], v[66:69], v[4:7]
	s_waitcnt lgkmcnt(4)
	v_mfma_f32_16x16x32_bf16 v[20:23], v[16:19], v[70:73], v[4:7]
	s_waitcnt lgkmcnt(3)
	v_mfma_f32_16x16x32_bf16 v[4:7], v[106:109], v[0:3], 0
	s_waitcnt lgkmcnt(2)
	v_mfma_f32_16x16x32_bf16 v[4:7], v[110:113], v[62:65], v[4:7]
	s_waitcnt lgkmcnt(1)
	v_mfma_f32_16x16x32_bf16 v[4:7], v[114:117], v[66:69], v[4:7]
	s_waitcnt lgkmcnt(0)
	v_mfma_f32_16x16x32_bf16 v[16:19], v[118:121], v[70:73], v[4:7]
	s_nop 5
	ds_read_b128 v[4:7], v126 offset:52224
	ds_read_b128 v[8:11], v126 offset:52288
	ds_read_b128 v[12:15], v126 offset:52352
	ds_read_b128 v[106:109], v126 offset:52416
	ds_read_b128 v[110:113], v126 offset:56576
	ds_read_b128 v[114:117], v126 offset:56640
	ds_read_b128 v[118:121], v126 offset:56704
	ds_read_b128 v[122:125], v126 offset:56768
	s_waitcnt lgkmcnt(7)
	v_mfma_f32_16x16x32_bf16 v[4:7], v[4:7], v[0:3], 0
	s_waitcnt lgkmcnt(6)
	v_mfma_f32_16x16x32_bf16 v[4:7], v[8:11], v[62:65], v[4:7]
	s_waitcnt lgkmcnt(5)
	v_mfma_f32_16x16x32_bf16 v[4:7], v[12:15], v[66:69], v[4:7]
	s_waitcnt lgkmcnt(4)
	v_mfma_f32_16x16x32_bf16 v[12:15], v[106:109], v[70:73], v[4:7]
	s_waitcnt lgkmcnt(3)
	v_mfma_f32_16x16x32_bf16 v[4:7], v[110:113], v[0:3], 0
	s_waitcnt lgkmcnt(2)
	v_mfma_f32_16x16x32_bf16 v[4:7], v[114:117], v[62:65], v[4:7]
	s_waitcnt lgkmcnt(1)
	v_mfma_f32_16x16x32_bf16 v[4:7], v[118:121], v[66:69], v[4:7]
	s_waitcnt lgkmcnt(0)
	v_mfma_f32_16x16x32_bf16 v[8:11], v[122:125], v[70:73], v[4:7]
	v_or_b32_e32 v118, 0xf0, v98
	v_mad_u32_u24 v32, v118, s33, v32
	s_nop 3
	ds_read_b128 v[4:7], v126 offset:60928
	ds_read_b128 v[106:109], v126 offset:60992
	ds_read_b128 v[110:113], v126 offset:61056
	ds_read_b128 v[114:117], v126 offset:61120
	ds_read_b128 v[118:121], v32
	ds_read_b128 v[122:125], v32 offset:64
	ds_read_b128 v[126:129], v32 offset:128
	ds_read_b128 v[130:133], v32 offset:192
	s_waitcnt lgkmcnt(7)
	v_mfma_f32_16x16x32_bf16 v[4:7], v[4:7], v[0:3], 0
	s_waitcnt lgkmcnt(3)
	v_mfma_f32_16x16x32_bf16 v[0:3], v[118:121], v[0:3], 0
	v_mfma_f32_16x16x32_bf16 v[4:7], v[106:109], v[62:65], v[4:7]
	s_waitcnt lgkmcnt(2)
	v_mfma_f32_16x16x32_bf16 v[0:3], v[122:125], v[62:65], v[0:3]
	v_mfma_f32_16x16x32_bf16 v[4:7], v[110:113], v[66:69], v[4:7]
	s_waitcnt lgkmcnt(1)
	v_mfma_f32_16x16x32_bf16 v[0:3], v[126:129], v[66:69], v[0:3]
	v_mfma_f32_16x16x32_bf16 v[4:7], v[114:117], v[70:73], v[4:7]
	s_waitcnt lgkmcnt(0)
	v_mfma_f32_16x16x32_bf16 v[0:3], v[130:133], v[70:73], v[0:3]
	v_max_f32_e32 v32, v75, v75
	v_max_f32_e32 v62, v74, v74
	v_max_f32_e32 v32, v62, v32
	v_max_f32_e32 v62, v77, v77
	v_max_f32_e32 v63, v76, v76
	v_max_f32_e32 v62, v63, v62
	s_mov_b32 s8, 0xff61b1e6
	v_max3_f32 v32, v32, v62, s8
	v_max_f32_e32 v62, v59, v59
	v_max_f32_e32 v63, v58, v58
	v_max_f32_e32 v62, v63, v62
	v_max_f32_e32 v63, v61, v61
	v_max_f32_e32 v64, v60, v60
	v_max_f32_e32 v63, v64, v63
	v_max3_f32 v32, v62, v63, v32
	v_max_f32_e32 v62, v55, v55
	v_max_f32_e32 v63, v54, v54
	v_max_f32_e32 v62, v63, v62
	v_max_f32_e32 v63, v57, v57
	v_max_f32_e32 v64, v56, v56
	v_max_f32_e32 v63, v64, v63
	v_max3_f32 v32, v62, v63, v32
	v_max_f32_e32 v62, v51, v51
	v_max_f32_e32 v63, v50, v50
	v_max_f32_e32 v62, v63, v62
	v_max_f32_e32 v63, v53, v53
	v_max_f32_e32 v64, v52, v52
	v_max_f32_e32 v63, v64, v63
	v_max3_f32 v32, v62, v63, v32
	v_max_f32_e32 v62, v47, v47
	v_max_f32_e32 v63, v46, v46
	v_max_f32_e32 v62, v63, v62
	v_max_f32_e32 v63, v49, v49
	v_max_f32_e32 v64, v48, v48
	v_max_f32_e32 v63, v64, v63
	v_max3_f32 v32, v62, v63, v32
	v_max_f32_e32 v62, v43, v43
	v_max_f32_e32 v63, v42, v42
	v_max_f32_e32 v62, v63, v62
	v_max_f32_e32 v63, v45, v45
	v_max_f32_e32 v64, v44, v44
	v_max_f32_e32 v63, v64, v63
	v_max3_f32 v32, v62, v63, v32
	v_max_f32_e32 v62, v39, v39
	v_max_f32_e32 v63, v38, v38
	v_max_f32_e32 v62, v63, v62
	v_max_f32_e32 v63, v41, v41
	v_max_f32_e32 v64, v40, v40
	v_max_f32_e32 v63, v64, v63
	v_max3_f32 v32, v62, v63, v32
	v_max_f32_e32 v62, v35, v35
	v_max_f32_e32 v63, v34, v34
	v_max_f32_e32 v62, v63, v62
	v_max_f32_e32 v63, v37, v37
	v_max_f32_e32 v64, v36, v36
	v_max_f32_e32 v63, v64, v63
	v_max3_f32 v32, v62, v63, v32
	v_max_f32_e32 v62, v29, v29
	v_max_f32_e32 v63, v28, v28
	v_max_f32_e32 v62, v63, v62
	v_max_f32_e32 v63, v31, v31
	v_max_f32_e32 v64, v30, v30
	v_max_f32_e32 v63, v64, v63
	v_max3_f32 v32, v62, v63, v32
	v_max_f32_e32 v62, v25, v25
	v_max_f32_e32 v63, v24, v24
	v_max_f32_e32 v62, v63, v62
	v_max_f32_e32 v63, v27, v27
	v_max_f32_e32 v64, v26, v26
	v_max_f32_e32 v63, v64, v63
	v_max3_f32 v32, v62, v63, v32
	v_max_f32_e32 v62, v21, v21
	v_max_f32_e32 v63, v20, v20
	v_max_f32_e32 v62, v63, v62
	v_max_f32_e32 v63, v23, v23
	v_max_f32_e32 v64, v22, v22
	v_max_f32_e32 v63, v64, v63
	v_max3_f32 v32, v62, v63, v32
	v_max_f32_e32 v62, v17, v17
	v_max_f32_e32 v63, v16, v16
	v_max_f32_e32 v62, v63, v62
	v_max_f32_e32 v63, v19, v19
	v_max_f32_e32 v64, v18, v18
	v_max_f32_e32 v63, v64, v63
	v_max3_f32 v32, v62, v63, v32
	v_max_f32_e32 v62, v13, v13
	v_max_f32_e32 v63, v12, v12
	v_max_f32_e32 v62, v63, v62
	v_max_f32_e32 v63, v15, v15
	v_max_f32_e32 v64, v14, v14
	v_max_f32_e32 v63, v64, v63
	v_max3_f32 v32, v62, v63, v32
	v_max_f32_e32 v62, v9, v9
	v_max_f32_e32 v63, v8, v8
	v_max_f32_e32 v62, v63, v62
	v_max_f32_e32 v63, v11, v11
	v_max_f32_e32 v64, v10, v10
	v_max_f32_e32 v63, v64, v63
	v_max3_f32 v32, v62, v63, v32
	v_max_f32_e32 v62, v5, v5
	v_max_f32_e32 v63, v4, v4
	v_max_f32_e32 v62, v63, v62
	v_max_f32_e32 v63, v7, v7
	v_max_f32_e32 v64, v6, v6
	v_max_f32_e32 v63, v64, v63
	v_max3_f32 v32, v62, v63, v32
	v_max_f32_e32 v62, v1, v1
	v_max_f32_e32 v63, v0, v0
	v_max_f32_e32 v62, v63, v62
	v_max_f32_e32 v63, v3, v3
	v_max_f32_e32 v64, v2, v2
	v_max_f32_e32 v63, v64, v63
	v_max3_f32 v32, v62, v63, v32
	ds_bpermute_b32 v62, v100, v32
	s_waitcnt lgkmcnt(0)
	v_max_f32_e32 v62, v62, v62
	v_max_f32_e32 v32, v32, v62
	ds_bpermute_b32 v62, v101, v32
	s_waitcnt lgkmcnt(0)
	v_max_f32_e32 v62, v62, v62
	v_max_f32_e32 v66, v32, v62
	v_sub_f32_e32 v32, v74, v66
	v_exp_f32_e32 v62, v32
	v_sub_f32_e32 v63, v75, v66
	v_exp_f32_e32 v63, v63
	v_sub_f32_e32 v64, v76, v66
	v_exp_f32_e32 v64, v64
	v_sub_f32_e32 v65, v77, v66
	v_exp_f32_e32 v65, v65
	v_sub_f32_e32 v58, v58, v66
	v_add_f32_e32 v32, 0, v62
	v_exp_f32_e32 v67, v58
	v_sub_f32_e32 v58, v59, v66
	v_add_f32_e32 v32, v63, v32
	v_exp_f32_e32 v68, v58
	v_sub_f32_e32 v58, v60, v66
	v_add_f32_e32 v32, v64, v32
	v_exp_f32_e32 v60, v58
	v_sub_f32_e32 v58, v61, v66
	v_add_f32_e32 v32, v65, v32
	v_exp_f32_e32 v61, v58
	v_sub_f32_e32 v54, v54, v66
	v_add_f32_e32 v32, v67, v32
	v_exp_f32_e32 v54, v54
	v_sub_f32_e32 v55, v55, v66
	v_add_f32_e32 v32, v68, v32
	v_exp_f32_e32 v55, v55
	v_sub_f32_e32 v56, v56, v66
	v_add_f32_e32 v32, v60, v32
	v_exp_f32_e32 v56, v56
	v_sub_f32_e32 v57, v57, v66
	v_add_f32_e32 v32, v61, v32
	v_exp_f32_e32 v57, v57
	v_sub_f32_e32 v50, v50, v66
	v_add_f32_e32 v32, v54, v32
	v_exp_f32_e32 v58, v50
	v_sub_f32_e32 v50, v51, v66
	v_add_f32_e32 v32, v55, v32
	v_exp_f32_e32 v59, v50
	v_sub_f32_e32 v50, v52, v66
	v_add_f32_e32 v32, v56, v32
	v_exp_f32_e32 v52, v50
	v_sub_f32_e32 v50, v53, v66
	v_add_f32_e32 v32, v57, v32
	v_exp_f32_e32 v53, v50
	v_sub_f32_e32 v46, v46, v66
	v_add_f32_e32 v32, v58, v32
	v_exp_f32_e32 v46, v46
	v_sub_f32_e32 v47, v47, v66
	v_add_f32_e32 v32, v59, v32
	v_exp_f32_e32 v47, v47
	v_sub_f32_e32 v48, v48, v66
	v_add_f32_e32 v32, v52, v32
	v_exp_f32_e32 v48, v48
	v_sub_f32_e32 v49, v49, v66
	v_add_f32_e32 v32, v53, v32
	v_exp_f32_e32 v49, v49
	v_sub_f32_e32 v42, v42, v66
	v_add_f32_e32 v32, v46, v32
	v_exp_f32_e32 v50, v42
	v_sub_f32_e32 v42, v43, v66
	v_add_f32_e32 v32, v47, v32
	v_exp_f32_e32 v51, v42
	v_sub_f32_e32 v42, v44, v66
	v_add_f32_e32 v32, v48, v32
	v_exp_f32_e32 v44, v42
	v_sub_f32_e32 v42, v45, v66
	v_add_f32_e32 v32, v49, v32
	v_exp_f32_e32 v45, v42
	v_sub_f32_e32 v38, v38, v66
	v_add_f32_e32 v32, v50, v32
	v_exp_f32_e32 v38, v38
	v_sub_f32_e32 v39, v39, v66
	v_add_f32_e32 v32, v51, v32
	v_exp_f32_e32 v39, v39
	v_sub_f32_e32 v40, v40, v66
	v_add_f32_e32 v32, v44, v32
	v_exp_f32_e32 v40, v40
	v_sub_f32_e32 v41, v41, v66
	v_add_f32_e32 v32, v45, v32
	v_exp_f32_e32 v41, v41
	v_sub_f32_e32 v34, v34, v66
	v_add_f32_e32 v32, v38, v32
	v_exp_f32_e32 v42, v34
	v_sub_f32_e32 v34, v35, v66
	v_add_f32_e32 v32, v39, v32
	v_exp_f32_e32 v43, v34
	v_sub_f32_e32 v34, v36, v66
	v_add_f32_e32 v32, v40, v32
	v_exp_f32_e32 v36, v34
	v_sub_f32_e32 v34, v37, v66
	v_add_f32_e32 v32, v41, v32
	v_exp_f32_e32 v37, v34
	v_sub_f32_e32 v28, v28, v66
	v_add_f32_e32 v32, v42, v32
	v_exp_f32_e32 v28, v28
	v_sub_f32_e32 v29, v29, v66
	v_add_f32_e32 v32, v43, v32
	v_exp_f32_e32 v29, v29
	v_sub_f32_e32 v30, v30, v66
	v_add_f32_e32 v32, v36, v32
	v_exp_f32_e32 v30, v30
	v_sub_f32_e32 v31, v31, v66
	v_add_f32_e32 v32, v37, v32
	v_exp_f32_e32 v31, v31
	v_add_f32_e32 v32, v28, v32
	v_add_f32_e32 v32, v29, v32
	v_add_f32_e32 v32, v30, v32
	v_sub_f32_e32 v24, v24, v66
	v_add_f32_e32 v34, v31, v32
	v_exp_f32_e32 v32, v24
	v_sub_f32_e32 v25, v25, v66
	v_sub_f32_e32 v20, v20, v66
	v_exp_f32_e32 v20, v20
	v_add_f32_e32 v24, v32, v34
	v_exp_f32_e32 v34, v25
	v_sub_f32_e32 v25, v26, v66
	v_exp_f32_e32 v35, v25
	v_sub_f32_e32 v25, v27, v66
	v_exp_f32_e32 v27, v25
	v_sub_f32_e32 v21, v21, v66
	v_add_f32_e32 v24, v34, v24
	v_exp_f32_e32 v21, v21
	v_sub_f32_e32 v22, v22, v66
	v_add_f32_e32 v24, v35, v24
	v_exp_f32_e32 v22, v22
	v_sub_f32_e32 v23, v23, v66
	v_add_f32_e32 v24, v27, v24
	v_exp_f32_e32 v23, v23
	v_add_f32_e32 v24, v20, v24
	v_add_f32_e32 v24, v21, v24
	v_add_f32_e32 v24, v22, v24
	v_sub_f32_e32 v16, v16, v66
	v_add_f32_e32 v25, v23, v24
	v_exp_f32_e32 v24, v16
	v_sub_f32_e32 v17, v17, v66
	v_sub_f32_e32 v12, v12, v66
	v_exp_f32_e32 v12, v12
	v_add_f32_e32 v16, v24, v25
	v_exp_f32_e32 v25, v17
	v_sub_f32_e32 v17, v18, v66
	v_exp_f32_e32 v26, v17
	v_sub_f32_e32 v17, v19, v66
	v_exp_f32_e32 v19, v17
	v_sub_f32_e32 v13, v13, v66
	v_add_f32_e32 v16, v25, v16
	v_exp_f32_e32 v13, v13
	v_sub_f32_e32 v14, v14, v66
	v_add_f32_e32 v16, v26, v16
	v_exp_f32_e32 v14, v14
	v_sub_f32_e32 v15, v15, v66
	v_add_f32_e32 v16, v19, v16
	v_exp_f32_e32 v15, v15
	v_add_f32_e32 v16, v12, v16
	v_add_f32_e32 v16, v13, v16
	v_add_f32_e32 v16, v14, v16
	v_sub_f32_e32 v8, v8, v66
	v_add_f32_e32 v17, v15, v16
	v_exp_f32_e32 v16, v8
	v_sub_f32_e32 v9, v9, v66
	v_sub_f32_e32 v4, v4, v66
	v_exp_f32_e32 v4, v4
	v_add_f32_e32 v8, v16, v17
	v_exp_f32_e32 v17, v9
	v_sub_f32_e32 v9, v10, v66
	v_exp_f32_e32 v18, v9
	v_sub_f32_e32 v9, v11, v66
	v_exp_f32_e32 v11, v9
	v_sub_f32_e32 v5, v5, v66
	v_add_f32_e32 v8, v17, v8
	v_exp_f32_e32 v5, v5
	v_sub_f32_e32 v6, v6, v66
	v_add_f32_e32 v8, v18, v8
	v_exp_f32_e32 v6, v6
	v_sub_f32_e32 v7, v7, v66
	v_add_f32_e32 v8, v11, v8
	v_exp_f32_e32 v7, v7
	v_add_f32_e32 v8, v4, v8
	v_add_f32_e32 v8, v5, v8
	v_add_f32_e32 v8, v6, v8
	v_sub_f32_e32 v0, v0, v66
	v_add_f32_e32 v9, v7, v8
	v_exp_f32_e32 v8, v0
	v_sub_f32_e32 v1, v1, v66
	v_cvt_pk_bf16_f32 v62, v62, v63
	v_cvt_pk_bf16_f32 v63, v64, v65
	v_add_f32_e32 v0, v8, v9
	v_exp_f32_e32 v9, v1
	v_sub_f32_e32 v1, v2, v66
	v_exp_f32_e32 v10, v1
	v_sub_f32_e32 v1, v3, v66
	v_lshlrev_b32_e32 v66, 3, v98
	v_mul_u32_u24_e32 v2, 0x120, v105
	v_and_b32_e32 v66, 24, v66
	v_add3_u32 v2, s27, v2, v66
	v_cvt_pk_bf16_f32 v64, v67, v68
	ds_read_b64_tr_b16 v[68:69], v2 offset:4608
	ds_read_b64_tr_b16 v[66:67], v2
	ds_read_b64_tr_b16 v[70:71], v2 offset:32
	ds_read_b64_tr_b16 v[72:73], v2 offset:4640
	ds_read_b64_tr_b16 v[74:75], v2 offset:64
	ds_read_b64_tr_b16 v[76:77], v2 offset:4672
	ds_read_b64_tr_b16 v[106:107], v2 offset:96
	ds_read_b64_tr_b16 v[108:109], v2 offset:4704
	ds_read_b64_tr_b16 v[110:111], v2 offset:128
	ds_read_b64_tr_b16 v[112:113], v2 offset:4736
	ds_read_b64_tr_b16 v[114:115], v2 offset:160
	ds_read_b64_tr_b16 v[116:117], v2 offset:4768
	ds_read_b64_tr_b16 v[118:119], v2 offset:192
	ds_read_b64_tr_b16 v[120:121], v2 offset:4800
	ds_read_b64_tr_b16 v[122:123], v2 offset:224
	ds_read_b64_tr_b16 v[124:125], v2 offset:4832
	v_exp_f32_e32 v3, v1
	v_add_f32_e32 v0, v9, v0
	v_add_f32_e32 v0, v10, v0
	v_cvt_pk_bf16_f32 v65, v60, v61
	v_add_f32_e32 v0, v3, v0
	ds_bpermute_b32 v1, v100, v0
	s_waitcnt lgkmcnt(0)
	v_add_f32_e32 v0, v0, v1
	ds_bpermute_b32 v1, v101, v0
	v_mfma_f32_16x16x32_bf16 v[66:69], v[66:69], v[62:65], 0
	v_mfma_f32_16x16x32_bf16 v[70:73], v[70:73], v[62:65], 0
	v_mfma_f32_16x16x32_bf16 v[74:77], v[74:77], v[62:65], 0
	v_mfma_f32_16x16x32_bf16 v[106:109], v[106:109], v[62:65], 0
	v_mfma_f32_16x16x32_bf16 v[110:113], v[110:113], v[62:65], 0
	v_mfma_f32_16x16x32_bf16 v[114:117], v[114:117], v[62:65], 0
	v_mfma_f32_16x16x32_bf16 v[118:121], v[118:121], v[62:65], 0
	v_mfma_f32_16x16x32_bf16 v[60:63], v[122:125], v[62:65], 0
	ds_read_b64_tr_b16 v[124:125], v2 offset:13824
	ds_read_b64_tr_b16 v[122:123], v2 offset:9216
	ds_read_b64_tr_b16 v[126:127], v2 offset:9248
	ds_read_b64_tr_b16 v[128:129], v2 offset:13856
	ds_read_b64_tr_b16 v[130:131], v2 offset:9280
	ds_read_b64_tr_b16 v[132:133], v2 offset:13888
	ds_read_b64_tr_b16 v[134:135], v2 offset:9312
	ds_read_b64_tr_b16 v[136:137], v2 offset:13920
	ds_read_b64_tr_b16 v[138:139], v2 offset:9344
	ds_read_b64_tr_b16 v[140:141], v2 offset:13952
	ds_read_b64_tr_b16 v[142:143], v2 offset:9376
	ds_read_b64_tr_b16 v[144:145], v2 offset:13984
	ds_read_b64_tr_b16 v[146:147], v2 offset:9408
	ds_read_b64_tr_b16 v[148:149], v2 offset:14016
	ds_read_b64_tr_b16 v[150:151], v2 offset:9440
	ds_read_b64_tr_b16 v[152:153], v2 offset:14048
	v_cvt_pk_bf16_f32 v54, v54, v55
	v_cvt_pk_bf16_f32 v55, v56, v57
	v_cvt_pk_bf16_f32 v56, v58, v59
	v_cvt_pk_bf16_f32 v57, v52, v53
	s_waitcnt lgkmcnt(14)
	v_mfma_f32_16x16x32_bf16 v[64:67], v[122:125], v[54:57], v[66:69]
	s_waitcnt lgkmcnt(12)
	v_mfma_f32_16x16x32_bf16 v[68:71], v[126:129], v[54:57], v[70:73]
	s_waitcnt lgkmcnt(10)
	v_mfma_f32_16x16x32_bf16 v[72:75], v[130:133], v[54:57], v[74:77]
	s_waitcnt lgkmcnt(8)
	v_mfma_f32_16x16x32_bf16 v[106:109], v[134:137], v[54:57], v[106:109]
	s_waitcnt lgkmcnt(6)
	v_mfma_f32_16x16x32_bf16 v[110:113], v[138:141], v[54:57], v[110:113]
	s_waitcnt lgkmcnt(4)
	v_mfma_f32_16x16x32_bf16 v[114:117], v[142:145], v[54:57], v[114:117]
	s_waitcnt lgkmcnt(2)
	v_mfma_f32_16x16x32_bf16 v[118:121], v[146:149], v[54:57], v[118:121]
	s_waitcnt lgkmcnt(0)
	v_mfma_f32_16x16x32_bf16 v[52:55], v[150:153], v[54:57], v[60:63]
	ds_read_b64_tr_b16 v[58:59], v2 offset:23040
	ds_read_b64_tr_b16 v[56:57], v2 offset:18432
	s_nop 0
	ds_read_b64_tr_b16 v[60:61], v2 offset:18464
	ds_read_b64_tr_b16 v[62:63], v2 offset:23072
	ds_read_b64_tr_b16 v[122:123], v2 offset:18496
	ds_read_b64_tr_b16 v[124:125], v2 offset:23104
	ds_read_b64_tr_b16 v[126:127], v2 offset:18528
	ds_read_b64_tr_b16 v[128:129], v2 offset:23136
	ds_read_b64_tr_b16 v[130:131], v2 offset:18560
	ds_read_b64_tr_b16 v[132:133], v2 offset:23168
	ds_read_b64_tr_b16 v[134:135], v2 offset:18592
	ds_read_b64_tr_b16 v[136:137], v2 offset:23200
	ds_read_b64_tr_b16 v[138:139], v2 offset:18624
	ds_read_b64_tr_b16 v[140:141], v2 offset:23232
	ds_read_b64_tr_b16 v[142:143], v2 offset:18656
	ds_read_b64_tr_b16 v[144:145], v2 offset:23264
	v_cvt_pk_bf16_f32 v46, v46, v47
	v_cvt_pk_bf16_f32 v47, v48, v49
	v_cvt_pk_bf16_f32 v48, v50, v51
	v_cvt_pk_bf16_f32 v49, v44, v45
	s_waitcnt lgkmcnt(14)
	v_mfma_f32_16x16x32_bf16 v[56:59], v[56:59], v[46:49], v[64:67]
	s_waitcnt lgkmcnt(12)
	v_mfma_f32_16x16x32_bf16 v[60:63], v[60:63], v[46:49], v[68:71]
	s_waitcnt lgkmcnt(10)
	v_mfma_f32_16x16x32_bf16 v[64:67], v[122:125], v[46:49], v[72:75]
	s_waitcnt lgkmcnt(8)
	v_mfma_f32_16x16x32_bf16 v[68:71], v[126:129], v[46:49], v[106:109]
	s_waitcnt lgkmcnt(6)
	v_mfma_f32_16x16x32_bf16 v[72:75], v[130:133], v[46:49], v[110:113]
	s_waitcnt lgkmcnt(4)
	v_mfma_f32_16x16x32_bf16 v[106:109], v[134:137], v[46:49], v[114:117]
	s_waitcnt lgkmcnt(2)
	v_mfma_f32_16x16x32_bf16 v[110:113], v[138:141], v[46:49], v[118:121]
	s_waitcnt lgkmcnt(0)
	v_mfma_f32_16x16x32_bf16 v[44:47], v[142:145], v[46:49], v[52:55]
	ds_read_b64_tr_b16 v[50:51], v2 offset:32256
	ds_read_b64_tr_b16 v[48:49], v2 offset:27648
	s_nop 0
	ds_read_b64_tr_b16 v[52:53], v2 offset:27680
	ds_read_b64_tr_b16 v[54:55], v2 offset:32288
	ds_read_b64_tr_b16 v[114:115], v2 offset:27712
	ds_read_b64_tr_b16 v[116:117], v2 offset:32320
	ds_read_b64_tr_b16 v[118:119], v2 offset:27744
	ds_read_b64_tr_b16 v[120:121], v2 offset:32352
	ds_read_b64_tr_b16 v[122:123], v2 offset:27776
	ds_read_b64_tr_b16 v[124:125], v2 offset:32384
	ds_read_b64_tr_b16 v[126:127], v2 offset:27808
	ds_read_b64_tr_b16 v[128:129], v2 offset:32416
	ds_read_b64_tr_b16 v[130:131], v2 offset:27840
	ds_read_b64_tr_b16 v[132:133], v2 offset:32448
	ds_read_b64_tr_b16 v[134:135], v2 offset:27872
	ds_read_b64_tr_b16 v[136:137], v2 offset:32480
	v_cvt_pk_bf16_f32 v38, v38, v39
	v_cvt_pk_bf16_f32 v39, v40, v41
	v_cvt_pk_bf16_f32 v40, v42, v43
	v_cvt_pk_bf16_f32 v41, v36, v37
	s_waitcnt lgkmcnt(14)
	v_mfma_f32_16x16x32_bf16 v[48:51], v[48:51], v[38:41], v[56:59]
	s_waitcnt lgkmcnt(12)
	v_mfma_f32_16x16x32_bf16 v[52:55], v[52:55], v[38:41], v[60:63]
	s_waitcnt lgkmcnt(10)
	v_mfma_f32_16x16x32_bf16 v[56:59], v[114:117], v[38:41], v[64:67]
	s_waitcnt lgkmcnt(8)
	v_mfma_f32_16x16x32_bf16 v[60:63], v[118:121], v[38:41], v[68:71]
	s_waitcnt lgkmcnt(6)
	v_mfma_f32_16x16x32_bf16 v[64:67], v[122:125], v[38:41], v[72:75]
	s_waitcnt lgkmcnt(4)
	v_mfma_f32_16x16x32_bf16 v[68:71], v[126:129], v[38:41], v[106:109]
	s_waitcnt lgkmcnt(2)
	v_mfma_f32_16x16x32_bf16 v[72:75], v[130:133], v[38:41], v[110:113]
	s_waitcnt lgkmcnt(0)
	v_mfma_f32_16x16x32_bf16 v[36:39], v[134:137], v[38:41], v[44:47]
	ds_read_b64_tr_b16 v[42:43], v2 offset:41472
	ds_read_b64_tr_b16 v[40:41], v2 offset:36864
	s_nop 0
	ds_read_b64_tr_b16 v[44:45], v2 offset:36896
	ds_read_b64_tr_b16 v[46:47], v2 offset:41504
	ds_read_b64_tr_b16 v[106:107], v2 offset:36928
	ds_read_b64_tr_b16 v[108:109], v2 offset:41536
	ds_read_b64_tr_b16 v[110:111], v2 offset:36960
	ds_read_b64_tr_b16 v[112:113], v2 offset:41568
	ds_read_b64_tr_b16 v[114:115], v2 offset:36992
	ds_read_b64_tr_b16 v[116:117], v2 offset:41600
	ds_read_b64_tr_b16 v[118:119], v2 offset:37024
	ds_read_b64_tr_b16 v[120:121], v2 offset:41632
	ds_read_b64_tr_b16 v[122:123], v2 offset:37056
	ds_read_b64_tr_b16 v[124:125], v2 offset:41664
	ds_read_b64_tr_b16 v[126:127], v2 offset:37088
	ds_read_b64_tr_b16 v[128:129], v2 offset:41696
	v_cvt_pk_bf16_f32 v28, v28, v29
	v_cvt_pk_bf16_f32 v29, v30, v31
	v_cvt_pk_bf16_f32 v30, v32, v34
	v_cvt_pk_bf16_f32 v31, v35, v27
	s_waitcnt lgkmcnt(14)
	v_mfma_f32_16x16x32_bf16 v[40:43], v[40:43], v[28:31], v[48:51]
	s_waitcnt lgkmcnt(12)
	v_mfma_f32_16x16x32_bf16 v[44:47], v[44:47], v[28:31], v[52:55]
	s_waitcnt lgkmcnt(10)
	v_mfma_f32_16x16x32_bf16 v[48:51], v[106:109], v[28:31], v[56:59]
	s_waitcnt lgkmcnt(8)
	v_mfma_f32_16x16x32_bf16 v[52:55], v[110:113], v[28:31], v[60:63]
	s_waitcnt lgkmcnt(6)
	v_mfma_f32_16x16x32_bf16 v[56:59], v[114:117], v[28:31], v[64:67]
	s_waitcnt lgkmcnt(4)
	v_mfma_f32_16x16x32_bf16 v[60:63], v[118:121], v[28:31], v[68:71]
	s_waitcnt lgkmcnt(2)
	v_mfma_f32_16x16x32_bf16 v[64:67], v[122:125], v[28:31], v[72:75]
	s_waitcnt lgkmcnt(0)
	v_mfma_f32_16x16x32_bf16 v[28:31], v[126:129], v[28:31], v[36:39]
	v_cvt_pk_bf16_f32 v20, v20, v21
	v_cvt_pk_bf16_f32 v21, v22, v23
	v_cvt_pk_bf16_f32 v22, v24, v25
	v_cvt_pk_bf16_f32 v23, v26, v19
	ds_read_b64_tr_b16 v[26:27], v2 offset:50688
	ds_read_b64_tr_b16 v[24:25], v2 offset:46080
	ds_read_b64_tr_b16 v[34:35], v2 offset:46112
	ds_read_b64_tr_b16 v[36:37], v2 offset:50720
	ds_read_b64_tr_b16 v[68:69], v2 offset:46144
	ds_read_b64_tr_b16 v[70:71], v2 offset:50752
	ds_read_b64_tr_b16 v[72:73], v2 offset:46176
	ds_read_b64_tr_b16 v[74:75], v2 offset:50784
	ds_read_b64_tr_b16 v[106:107], v2 offset:46208
	ds_read_b64_tr_b16 v[108:109], v2 offset:50816
	ds_read_b64_tr_b16 v[110:111], v2 offset:46240
	ds_read_b64_tr_b16 v[112:113], v2 offset:50848
	ds_read_b64_tr_b16 v[114:115], v2 offset:46272
	ds_read_b64_tr_b16 v[116:117], v2 offset:50880
	ds_read_b64_tr_b16 v[118:119], v2 offset:46304
	ds_read_b64_tr_b16 v[120:121], v2 offset:50912
	s_waitcnt lgkmcnt(14)
	v_mfma_f32_16x16x32_bf16 v[24:27], v[24:27], v[20:23], v[40:43]
	s_waitcnt lgkmcnt(12)
	v_mfma_f32_16x16x32_bf16 v[34:37], v[34:37], v[20:23], v[44:47]
	s_waitcnt lgkmcnt(10)
	v_mfma_f32_16x16x32_bf16 v[38:41], v[68:71], v[20:23], v[48:51]
	s_waitcnt lgkmcnt(8)
	v_mfma_f32_16x16x32_bf16 v[42:45], v[72:75], v[20:23], v[52:55]
	s_waitcnt lgkmcnt(6)
	v_mfma_f32_16x16x32_bf16 v[46:49], v[106:109], v[20:23], v[56:59]
	s_waitcnt lgkmcnt(4)
	v_mfma_f32_16x16x32_bf16 v[50:53], v[110:113], v[20:23], v[60:63]
	s_waitcnt lgkmcnt(2)
	v_mfma_f32_16x16x32_bf16 v[54:57], v[114:117], v[20:23], v[64:67]
	s_waitcnt lgkmcnt(0)
	v_mfma_f32_16x16x32_bf16 v[20:23], v[118:121], v[20:23], v[28:31]
	v_cvt_pk_bf16_f32 v12, v12, v13
	v_cvt_pk_bf16_f32 v13, v14, v15
	v_cvt_pk_bf16_f32 v14, v16, v17
	v_cvt_pk_bf16_f32 v15, v18, v11
	ds_read_b64_tr_b16 v[18:19], v2 offset:59904
	ds_read_b64_tr_b16 v[16:17], v2 offset:55296
	s_nop 0
	ds_read_b64_tr_b16 v[28:29], v2 offset:55328
	ds_read_b64_tr_b16 v[30:31], v2 offset:59936
	ds_read_b64_tr_b16 v[58:59], v2 offset:55360
	ds_read_b64_tr_b16 v[60:61], v2 offset:59968
	ds_read_b64_tr_b16 v[62:63], v2 offset:55392
	ds_read_b64_tr_b16 v[64:65], v2 offset:60000
	ds_read_b64_tr_b16 v[66:67], v2 offset:55424
	ds_read_b64_tr_b16 v[68:69], v2 offset:60032
	ds_read_b64_tr_b16 v[70:71], v2 offset:55456
	ds_read_b64_tr_b16 v[72:73], v2 offset:60064
	ds_read_b64_tr_b16 v[74:75], v2 offset:55488
	ds_read_b64_tr_b16 v[76:77], v2 offset:60096
	ds_read_b64_tr_b16 v[106:107], v2 offset:55520
	ds_read_b64_tr_b16 v[108:109], v2 offset:60128
	s_waitcnt lgkmcnt(14)
	v_mfma_f32_16x16x32_bf16 v[16:19], v[16:19], v[12:15], v[24:27]
	s_waitcnt lgkmcnt(12)
	v_mfma_f32_16x16x32_bf16 v[24:27], v[28:31], v[12:15], v[34:37]
	s_waitcnt lgkmcnt(10)
	v_mfma_f32_16x16x32_bf16 v[28:31], v[58:61], v[12:15], v[38:41]
	s_waitcnt lgkmcnt(8)
	v_mfma_f32_16x16x32_bf16 v[34:37], v[62:65], v[12:15], v[42:45]
	s_waitcnt lgkmcnt(6)
	v_mfma_f32_16x16x32_bf16 v[38:41], v[66:69], v[12:15], v[46:49]
	s_waitcnt lgkmcnt(4)
	v_mfma_f32_16x16x32_bf16 v[42:45], v[70:73], v[12:15], v[50:53]
	s_waitcnt lgkmcnt(2)
	v_mfma_f32_16x16x32_bf16 v[46:49], v[74:77], v[12:15], v[54:57]
	s_waitcnt lgkmcnt(0)
	v_mfma_f32_16x16x32_bf16 v[12:15], v[106:109], v[12:15], v[20:23]
	v_cvt_pk_bf16_f32 v4, v4, v5
	v_cvt_pk_bf16_f32 v5, v6, v7
	v_cvt_pk_bf16_f32 v7, v10, v3
	v_add_u32_e32 v3, 0x10e00, v2
	v_cvt_pk_bf16_f32 v6, v8, v9
	ds_read_b64_tr_b16 v[10:11], v3
	ds_read_b64_tr_b16 v[8:9], v2 offset:64512
	ds_read_b64_tr_b16 v[20:21], v2 offset:64544
	v_add_u32_e32 v3, 0x10e20, v2
	ds_read_b64_tr_b16 v[22:23], v3
	ds_read_b64_tr_b16 v[50:51], v2 offset:64576
	v_add_u32_e32 v3, 0x10e40, v2
	ds_read_b64_tr_b16 v[52:53], v3
	ds_read_b64_tr_b16 v[54:55], v2 offset:64608
	v_add_u32_e32 v3, 0x10e60, v2
	ds_read_b64_tr_b16 v[56:57], v3
	ds_read_b64_tr_b16 v[58:59], v2 offset:64640
	v_add_u32_e32 v3, 0x10e80, v2
	ds_read_b64_tr_b16 v[60:61], v3
	ds_read_b64_tr_b16 v[62:63], v2 offset:64672
	v_add_u32_e32 v3, 0x10ea0, v2
	ds_read_b64_tr_b16 v[64:65], v3
	ds_read_b64_tr_b16 v[66:67], v2 offset:64704
	v_add_u32_e32 v3, 0x10ec0, v2
	ds_read_b64_tr_b16 v[68:69], v3
	ds_read_b64_tr_b16 v[70:71], v2 offset:64736
	v_add_u32_e32 v2, 0x10ee0, v2
	ds_read_b64_tr_b16 v[72:73], v2
	s_waitcnt lgkmcnt(14)
	v_mfma_f32_16x16x32_bf16 v[8:11], v[8:11], v[4:7], v[16:19]
	s_waitcnt lgkmcnt(12)
	v_mfma_f32_16x16x32_bf16 v[16:19], v[20:23], v[4:7], v[24:27]
	s_waitcnt lgkmcnt(10)
	v_mfma_f32_16x16x32_bf16 v[20:23], v[50:53], v[4:7], v[28:31]
	s_waitcnt lgkmcnt(8)
	v_mfma_f32_16x16x32_bf16 v[24:27], v[54:57], v[4:7], v[34:37]
	s_waitcnt lgkmcnt(6)
	v_mfma_f32_16x16x32_bf16 v[28:31], v[58:61], v[4:7], v[38:41]
	s_waitcnt lgkmcnt(4)
	v_mfma_f32_16x16x32_bf16 v[34:37], v[62:65], v[4:7], v[42:45]
	s_waitcnt lgkmcnt(2)
	v_mfma_f32_16x16x32_bf16 v[38:41], v[66:69], v[4:7], v[46:49]
	s_waitcnt lgkmcnt(0)
	v_mfma_f32_16x16x32_bf16 v[2:5], v[70:73], v[4:7], v[12:15]
	v_add_f32_e32 v0, v0, v1
	v_rcp_f32_e32 v6, v0
	s_waitcnt vmcnt(7)
	v_lshlrev_b32_e32 v0, 16, v96
	v_and_b32_e32 v1, 0xffff0000, v96
	s_mov_b64 s[10:11], 0
	v_mul_f32_e32 v7, v6, v8
	v_mul_f32_e32 v8, v6, v9
	v_mul_f32_e32 v0, v7, v0
	v_mul_f32_e32 v1, v8, v1
	v_cvt_pk_bf16_f32 v0, v0, v1
	v_mul_f32_e32 v1, v6, v10
	v_lshlrev_b32_e32 v7, 16, v97
	v_mul_f32_e32 v1, v1, v7
	v_mul_f32_e32 v7, v6, v11
	v_and_b32_e32 v8, 0xffff0000, v97
	v_mul_f32_e32 v7, v7, v8
	v_cvt_pk_bf16_f32 v1, v1, v7
	global_store_dwordx2 v[94:95], v[0:1], off
	v_mul_f32_e32 v0, v6, v16
	s_waitcnt vmcnt(7)
	v_lshlrev_b32_e32 v1, 16, v92
	v_mul_f32_e32 v0, v0, v1
	v_mul_f32_e32 v1, v6, v17
	v_and_b32_e32 v7, 0xffff0000, v92
	v_mul_f32_e32 v1, v1, v7
	v_cvt_pk_bf16_f32 v0, v0, v1
	v_mul_f32_e32 v1, v6, v18
	v_lshlrev_b32_e32 v7, 16, v93
	v_mul_f32_e32 v1, v1, v7
	v_mul_f32_e32 v7, v6, v19
	v_and_b32_e32 v8, 0xffff0000, v93
	v_mul_f32_e32 v7, v7, v8
	v_cvt_pk_bf16_f32 v1, v1, v7
	global_store_dwordx2 v[78:79], v[0:1], off offset:32
	v_mul_f32_e32 v0, v6, v20
	s_waitcnt vmcnt(7)
	v_lshlrev_b32_e32 v1, 16, v90
	v_mul_f32_e32 v0, v0, v1
	v_mul_f32_e32 v1, v6, v21
	v_and_b32_e32 v7, 0xffff0000, v90
	v_mul_f32_e32 v1, v1, v7
	v_cvt_pk_bf16_f32 v0, v0, v1
	v_mul_f32_e32 v1, v6, v22
	v_lshlrev_b32_e32 v7, 16, v91
	v_mul_f32_e32 v1, v1, v7
	v_mul_f32_e32 v7, v6, v23
	v_and_b32_e32 v8, 0xffff0000, v91
	v_mul_f32_e32 v7, v7, v8
	v_cvt_pk_bf16_f32 v1, v1, v7
	global_store_dwordx2 v[78:79], v[0:1], off offset:64
	v_mul_f32_e32 v0, v6, v24
	s_waitcnt vmcnt(7)
	v_lshlrev_b32_e32 v1, 16, v88
	v_mul_f32_e32 v0, v0, v1
	v_mul_f32_e32 v1, v6, v25
	v_and_b32_e32 v7, 0xffff0000, v88
	v_mul_f32_e32 v1, v1, v7
	v_cvt_pk_bf16_f32 v0, v0, v1
	v_mul_f32_e32 v1, v6, v26
	v_lshlrev_b32_e32 v7, 16, v89
	v_mul_f32_e32 v1, v1, v7
	v_mul_f32_e32 v7, v6, v27
	v_and_b32_e32 v8, 0xffff0000, v89
	v_mul_f32_e32 v7, v7, v8
	v_cvt_pk_bf16_f32 v1, v1, v7
	global_store_dwordx2 v[78:79], v[0:1], off offset:96
	v_mul_f32_e32 v0, v6, v28
	s_waitcnt vmcnt(7)
	v_lshlrev_b32_e32 v1, 16, v86
	v_mul_f32_e32 v0, v0, v1
	v_mul_f32_e32 v1, v6, v29
	v_and_b32_e32 v7, 0xffff0000, v86
	v_mul_f32_e32 v1, v1, v7
	v_cvt_pk_bf16_f32 v0, v0, v1
	v_mul_f32_e32 v1, v6, v30
	v_lshlrev_b32_e32 v7, 16, v87
	v_mul_f32_e32 v1, v1, v7
	v_mul_f32_e32 v7, v6, v31
	v_and_b32_e32 v8, 0xffff0000, v87
	v_mul_f32_e32 v7, v7, v8
	v_cvt_pk_bf16_f32 v1, v1, v7
	global_store_dwordx2 v[78:79], v[0:1], off offset:128
	v_mul_f32_e32 v0, v6, v34
	s_waitcnt vmcnt(7)
	v_lshlrev_b32_e32 v1, 16, v84
	v_mul_f32_e32 v0, v0, v1
	v_mul_f32_e32 v1, v6, v35
	v_and_b32_e32 v7, 0xffff0000, v84
	v_mul_f32_e32 v1, v1, v7
	v_cvt_pk_bf16_f32 v0, v0, v1
	v_mul_f32_e32 v1, v6, v36
	v_lshlrev_b32_e32 v7, 16, v85
	v_mul_f32_e32 v1, v1, v7
	v_mul_f32_e32 v7, v6, v37
	v_and_b32_e32 v8, 0xffff0000, v85
	v_mul_f32_e32 v7, v7, v8
	v_cvt_pk_bf16_f32 v1, v1, v7
	global_store_dwordx2 v[78:79], v[0:1], off offset:160
	v_mul_f32_e32 v0, v6, v38
	s_waitcnt vmcnt(7)
	v_lshlrev_b32_e32 v1, 16, v82
	v_mul_f32_e32 v0, v0, v1
	v_mul_f32_e32 v1, v6, v39
	v_and_b32_e32 v7, 0xffff0000, v82
	v_mul_f32_e32 v1, v1, v7
	v_cvt_pk_bf16_f32 v0, v0, v1
	v_mul_f32_e32 v1, v6, v40
	v_lshlrev_b32_e32 v7, 16, v83
	v_mul_f32_e32 v1, v1, v7
	v_mul_f32_e32 v7, v6, v41
	v_and_b32_e32 v8, 0xffff0000, v83
	v_mul_f32_e32 v7, v7, v8
	v_cvt_pk_bf16_f32 v1, v1, v7
	global_store_dwordx2 v[78:79], v[0:1], off offset:192
	v_mul_f32_e32 v0, v6, v2
	s_waitcnt vmcnt(7)
	v_lshlrev_b32_e32 v1, 16, v80
	v_mul_f32_e32 v0, v0, v1
	v_mul_f32_e32 v1, v6, v3
	v_and_b32_e32 v2, 0xffff0000, v80
	v_mul_f32_e32 v1, v1, v2
	v_cvt_pk_bf16_f32 v0, v0, v1
	v_mul_f32_e32 v1, v6, v4
	v_lshlrev_b32_e32 v2, 16, v81
	v_mul_f32_e32 v1, v1, v2
	v_mul_f32_e32 v2, v6, v5
	v_and_b32_e32 v3, 0xffff0000, v81
	v_mul_f32_e32 v2, v2, v3
	v_cvt_pk_bf16_f32 v1, v1, v2
	global_store_dwordx2 v[78:79], v[0:1], off offset:224
	s_barrier
.LBB0_1276:
	s_andn2_b64 vcc, exec, s[10:11]
	s_cbranch_vccnz .LBB0_1313
	s_lshl_b32 s13, s74, 12
	v_readlane_b32 s8, v252, 59
	s_or_b32 s83, s8, s13
	s_lshl_b32 s28, s12, 1
	v_readlane_b32 s8, v252, 15
	s_add_u32 s8, s8, s28
	v_readlane_b32 s9, v252, 16
	v_lshlrev_b32_e32 v0, 4, v99
	s_addc_u32 s9, s9, 0
	v_readlane_b32 s10, v252, 17
	v_and_b32_e32 v32, 0xf0, v0
	s_add_u32 s10, s10, s28
	v_readlane_b32 s11, v252, 18
	v_lshl_add_u64 v[16:17], s[8:9], 0, v[32:33]
	v_readlane_b32 s8, v252, 60
	s_addc_u32 s11, s11, 0
	v_and_b32_e32 v0, -16, v99
	s_add_i32 s8, s8, s13
	v_lshl_add_u64 v[18:19], s[10:11], 0, v[32:33]
	v_add_u32_e32 v24, s8, v0
	s_movk_i32 s8, 0x80
	v_readlane_b32 s10, v252, 57
	v_cmp_gt_i32_e32 vcc, s8, v104
	v_readlane_b32 s11, v252, 58
	v_mov_b32_e32 v25, s83
	s_and_b64 vcc, s[10:11], vcc
	v_cndmask_b32_e32 v2, v24, v25, vcc
	v_mad_i64_i32 v[0:1], s[8:9], v2, s70, v[16:17]
	v_mad_i64_i32 v[4:5], s[8:9], v2, s70, v[18:19]
	s_movk_i32 s8, 0x60
	s_nop 0
	v_cmp_gt_i32_e32 vcc, s8, v104
	v_add_u32_e32 v8, 0x200, v24
	s_and_b64 vcc, s[10:11], vcc
	v_cndmask_b32_e32 v10, v8, v25, vcc
	v_cmp_gt_i32_e32 vcc, 64, v104
	v_add_u32_e32 v20, 0x400, v24
	s_and_b64 vcc, s[10:11], vcc
	v_cndmask_b32_e32 v22, v20, v25, vcc
	v_mad_i64_i32 v[8:9], s[8:9], v10, s70, v[16:17]
	v_mad_i64_i32 v[12:13], s[8:9], v10, s70, v[18:19]
	v_mad_i64_i32 v[20:21], s[8:9], v22, s70, v[16:17]
	v_cmp_gt_i32_e32 vcc, 32, v104
	s_nop 0
	s_nop 0
	s_nop 0
	v_mad_i64_i32 v[22:23], s[8:9], v22, s70, v[18:19]
	v_add_u32_e32 v20, 0x600, v24
	s_and_b64 vcc, s[10:11], vcc
	v_cndmask_b32_e32 v22, v20, v25, vcc
	v_mad_i64_i32 v[20:21], s[8:9], v22, s70, v[16:17]
	v_cmp_gt_i32_e32 vcc, 0, v104
	v_mad_i64_i32 v[22:23], s[8:9], v22, s70, v[18:19]
	v_add_u32_e32 v20, 0x800, v24
	s_and_b64 vcc, s[10:11], vcc
	v_cndmask_b32_e32 v22, v20, v25, vcc
	v_mad_i64_i32 v[20:21], s[8:9], v22, s70, v[16:17]
	v_mad_i64_i32 v[22:23], s[8:9], v22, s70, v[18:19]
	s_movk_i32 s8, 0xffe0
	s_nop 0
	v_cmp_gt_i32_e32 vcc, s8, v104
	v_add_u32_e32 v20, 0xa00, v24
	s_and_b64 vcc, s[10:11], vcc
	v_cndmask_b32_e32 v22, v20, v25, vcc
	v_mad_i64_i32 v[20:21], s[8:9], v22, s70, v[16:17]
	v_mad_i64_i32 v[22:23], s[8:9], v22, s70, v[18:19]
	s_movk_i32 s8, 0xffc0
	s_nop 0
	v_cmp_gt_i32_e32 vcc, s8, v104
	v_add_u32_e32 v20, 0xc00, v24
	s_and_b64 vcc, s[10:11], vcc
	v_cndmask_b32_e32 v22, v20, v25, vcc
	v_mad_i64_i32 v[20:21], s[8:9], v22, s70, v[16:17]
	v_mad_i64_i32 v[22:23], s[8:9], v22, s70, v[18:19]
	s_movk_i32 s8, 0xffa0
	s_nop 0
	v_cmp_gt_i32_e32 vcc, s8, v104
	v_add_u32_e32 v20, 0xe00, v24
	s_and_b64 vcc, s[10:11], vcc
	v_cndmask_b32_e32 v20, v20, v25, vcc
	v_mad_i64_i32 v[16:17], s[8:9], v20, s70, v[16:17]
	v_mad_i64_i32 v[18:19], s[8:9], v20, s70, v[18:19]
	v_readlane_b32 s8, v252, 19
	s_add_u32 s8, s8, s28
	v_readlane_b32 s9, v252, 20
	s_addc_u32 s9, s9, 0
	s_lshl_b32 s10, s73, 8
	v_lshlrev_b32_e32 v16, 4, v98
	v_and_b32_e32 v16, 0xf0, v16
	s_add_i32 s10, s10, s83
	v_or_b32_e32 v18, s10, v16
	v_mov_b64_e32 v[16:17], s[8:9]
	v_mad_i64_i32 v[16:17], s[8:9], v18, s70, v[16:17]
	v_and_b32_e32 v82, 48, v99
	v_mov_b32_e32 v83, v33
	v_lshl_add_u64 v[28:29], v[16:17], 0, v[82:83]
	s_nop 0
	v_add3_u32 v83, 0, v32, v102
	s_add_i32 s8, s73, -2
	v_add_u32_e32 v82, 0, v82
	s_cmp_gt_u32 s8, -11
	s_cselect_b64 s[44:45], -1, 0
	s_cmp_lt_u32 s8, -10
	v_add3_u32 v0, s27, v32, v103
	v_and_b32_e32 v32, 15, v99
	v_mov_b32_e32 v0, 0
	v_mad_u32_u24 v83, v32, s33, v82
	v_mov_b32_e32 v8, 0
	v_mov_b32_e32 v9, 0
	v_mov_b32_e32 v10, 0
	v_mov_b32_e32 v11, 0
	v_mov_b32_e32 v12, 0
	v_mov_b32_e32 v13, 0
	v_mov_b32_e32 v14, 0
	v_mov_b32_e32 v15, 0
	s_waitcnt lgkmcnt(0)
	s_cselect_b32 s49, 1, 0
	v_lshrrev_b32_e32 v227, 4, v218
	v_and_b32_e32 v244, 15, v218
	v_lshlrev_b32_e32 v244, 4, v244
	v_mul_u32_u24_e32 v245, 0x120, v227
	v_add3_u32 v245, s27, v244, v245
	v_mad_u32_u24 v244, v227, s33, v244
	s_cmp_lg_u32 s72, 0
	s_cbranch_scc1 .Lpf_wait_cnt2
	s_waitcnt vmcnt(0)
.Lpf_wait_cnt2:
	s_waitcnt vmcnt(8)
	ds_write_b128 v244, v[154:157]
	ds_write_b128 v245, v[158:161]
	ds_write_b128 v244, v[162:165] offset:8704
	ds_write_b128 v245, v[166:169] offset:9216
	ds_write_b128 v244, v[170:173] offset:17408
	ds_write_b128 v245, v[174:177] offset:18432
	ds_write_b128 v244, v[178:181] offset:26112
	ds_write_b128 v245, v[182:185] offset:27648
	ds_write_b128 v244, v[186:189] offset:34816
	ds_write_b128 v245, v[190:193] offset:36864
	ds_write_b128 v244, v[194:197] offset:43520
	ds_write_b128 v245, v[198:201] offset:46080
	ds_write_b128 v244, v[202:205] offset:52224
	ds_write_b128 v245, v[206:209] offset:55296
	ds_write_b128 v244, v[210:213] offset:60928
	ds_write_b128 v245, v[214:217] offset:64512
	v_mov_b64_e32 v[16:17], v[228:229]
	v_mov_b64_e32 v[18:19], v[230:231]
	v_mov_b64_e32 v[20:21], v[232:233]
	v_mov_b64_e32 v[22:23], v[234:235]
	v_mov_b64_e32 v[24:25], v[236:237]
	v_mov_b64_e32 v[26:27], v[238:239]
	v_mov_b64_e32 v[28:29], v[240:241]
	v_mov_b64_e32 v[30:31], v[242:243]
	s_add_u32 s48, s72, 1
	s_cmp_lt_u32 s48, 8
	s_cbranch_scc1 .Lpf_issue
.Lpf_ret_k2:
	s_waitcnt lgkmcnt(0)
	s_barrier
	s_cmp_lg_u32 s49, 0
	s_cbranch_scc1 .LBB0_1279
	ds_read_b128 v[2:5], v83
	ds_read_b128 v[6:9], v83 offset:64
	ds_read_b128 v[10:13], v83 offset:128
	ds_read_b128 v[34:37], v83 offset:192
	ds_read_b128 v[38:41], v83 offset:4352
	ds_read_b128 v[42:45], v83 offset:4416
	ds_read_b128 v[46:49], v83 offset:4480
	ds_read_b128 v[50:53], v83 offset:4544
	s_waitcnt lgkmcnt(7)
	v_mfma_f32_16x16x32_bf16 v[2:5], v[2:5], v[16:19], 0
	s_waitcnt lgkmcnt(6)
	v_mfma_f32_16x16x32_bf16 v[2:5], v[6:9], v[20:23], v[2:5]
	s_waitcnt lgkmcnt(5)
	v_mfma_f32_16x16x32_bf16 v[2:5], v[10:13], v[24:27], v[2:5]
	s_waitcnt lgkmcnt(4)
	v_mfma_f32_16x16x32_bf16 v[12:15], v[34:37], v[28:31], v[2:5]
	s_waitcnt lgkmcnt(3)
	v_mfma_f32_16x16x32_bf16 v[2:5], v[38:41], v[16:19], 0
	s_waitcnt lgkmcnt(2)
	v_mfma_f32_16x16x32_bf16 v[2:5], v[42:45], v[20:23], v[2:5]
	s_waitcnt lgkmcnt(1)
	v_mfma_f32_16x16x32_bf16 v[2:5], v[46:49], v[24:27], v[2:5]
	s_waitcnt lgkmcnt(0)
	v_mfma_f32_16x16x32_bf16 v[8:11], v[50:53], v[28:31], v[2:5]

.LBB0_1314:
	s_andn2_b64 vcc, exec, s[10:11]
	s_cbranch_vccnz .LBB0_1351
	s_lshl_b32 s12, s74, 12
	v_readlane_b32 s8, v252, 63
	s_lshl_b32 s77, s75, 7
	s_or_b32 s83, s8, s12
	s_and_b32 s8, s77, 0x180
	s_lshl_b32 s28, s8, 1
	v_readlane_b32 s8, v252, 15
	s_add_u32 s8, s8, s28
	v_readlane_b32 s9, v252, 16
	v_lshlrev_b32_e32 v0, 4, v99
	s_addc_u32 s9, s9, 0
	v_readlane_b32 s10, v252, 17
	v_and_b32_e32 v32, 0xf0, v0
	s_add_u32 s10, s10, s28
	v_readlane_b32 s11, v252, 18
	v_lshl_add_u64 v[16:17], s[8:9], 0, v[32:33]
	v_readlane_b32 s8, v253, 0
	s_addc_u32 s11, s11, 0
	v_ashrrev_i32_e32 v84, 4, v99
	s_add_i32 s8, s8, s12
	v_lshl_add_u64 v[18:19], s[10:11], 0, v[32:33]
	v_lshl_add_u32 v24, v84, 2, s8
	s_movk_i32 s8, 0x80
	v_readlane_b32 s10, v252, 61
	v_cmp_gt_i32_e32 vcc, s8, v84
	v_readlane_b32 s11, v252, 62
	v_mov_b32_e32 v25, s83
	s_and_b64 vcc, s[10:11], vcc
	v_cndmask_b32_e32 v2, v24, v25, vcc
	v_mad_i64_i32 v[0:1], s[8:9], v2, s70, v[16:17]
	v_mad_i64_i32 v[4:5], s[8:9], v2, s70, v[18:19]
	s_movk_i32 s8, 0x60
	s_nop 0
	v_cmp_gt_i32_e32 vcc, s8, v84
	v_add_u32_e32 v8, 0x80, v24
	s_and_b64 vcc, s[10:11], vcc
	v_cndmask_b32_e32 v10, v8, v25, vcc
	v_cmp_gt_i32_e32 vcc, 64, v84
	v_add_u32_e32 v20, 0x100, v24
	s_and_b64 vcc, s[10:11], vcc
	v_cndmask_b32_e32 v22, v20, v25, vcc
	v_mad_i64_i32 v[8:9], s[8:9], v10, s70, v[16:17]
	v_mad_i64_i32 v[12:13], s[8:9], v10, s70, v[18:19]
	v_mad_i64_i32 v[20:21], s[8:9], v22, s70, v[16:17]
	v_cmp_gt_i32_e32 vcc, 32, v84
	s_nop 0
	s_nop 0
	s_nop 0
	v_mad_i64_i32 v[22:23], s[8:9], v22, s70, v[18:19]
	v_add_u32_e32 v20, 0x180, v24
	s_and_b64 vcc, s[10:11], vcc
	v_cndmask_b32_e32 v22, v20, v25, vcc
	v_mad_i64_i32 v[20:21], s[8:9], v22, s70, v[16:17]
	v_cmp_gt_i32_e32 vcc, 0, v84
	v_mad_i64_i32 v[22:23], s[8:9], v22, s70, v[18:19]
	v_add_u32_e32 v20, 0x200, v24
	s_and_b64 vcc, s[10:11], vcc
	v_cndmask_b32_e32 v22, v20, v25, vcc
	v_mad_i64_i32 v[20:21], s[8:9], v22, s70, v[16:17]
	v_mad_i64_i32 v[22:23], s[8:9], v22, s70, v[18:19]
	s_movk_i32 s8, 0xffe0
	s_nop 0
	v_cmp_gt_i32_e32 vcc, s8, v84
	v_add_u32_e32 v20, 0x280, v24
	s_and_b64 vcc, s[10:11], vcc
	v_cndmask_b32_e32 v22, v20, v25, vcc
	v_mad_i64_i32 v[20:21], s[8:9], v22, s70, v[16:17]
	v_mad_i64_i32 v[22:23], s[8:9], v22, s70, v[18:19]
	s_movk_i32 s8, 0xffc0
	s_nop 0
	v_cmp_gt_i32_e32 vcc, s8, v84
	v_add_u32_e32 v20, 0x300, v24
	s_and_b64 vcc, s[10:11], vcc
	v_cndmask_b32_e32 v22, v20, v25, vcc
	v_mad_i64_i32 v[20:21], s[8:9], v22, s70, v[16:17]
	v_mad_i64_i32 v[22:23], s[8:9], v22, s70, v[18:19]
	s_movk_i32 s8, 0xffa0
	s_nop 0
	v_cmp_gt_i32_e32 vcc, s8, v84
	v_add_u32_e32 v20, 0x380, v24
	s_and_b64 vcc, s[10:11], vcc
	v_cndmask_b32_e32 v20, v20, v25, vcc
	v_mad_i64_i32 v[16:17], s[8:9], v20, s70, v[16:17]
	v_mad_i64_i32 v[18:19], s[8:9], v20, s70, v[18:19]
	v_readlane_b32 s8, v252, 23
	s_add_u32 s8, s8, s28
	v_readlane_b32 s9, v252, 24
	s_addc_u32 s9, s9, 0
	s_and_b32 s10, s76, 0xffffffc0
	v_lshlrev_b32_e32 v16, 2, v98
	s_add_i32 s10, s10, s83
	v_and_or_b32 v18, v16, 60, s10
	v_mov_b64_e32 v[16:17], s[8:9]
	v_mad_i64_i32 v[16:17], s[8:9], v18, s70, v[16:17]
	v_and_b32_e32 v82, 48, v99
	v_mov_b32_e32 v83, v33
	v_lshl_add_u64 v[28:29], v[16:17], 0, v[82:83]
	s_nop 0
	v_mul_lo_u32 v83, v84, s33
	v_add3_u32 v83, 0, v32, v83
	s_movk_i32 s8, 0x120
	v_add_u32_e32 v82, 0, v82
	v_mul_lo_u32 v0, v84, s8
	s_add_i32 s8, s73, -2
	v_add3_u32 v0, s27, v32, v0
	v_and_b32_e32 v32, 15, v99
	s_cmp_gt_u32 s8, -11
	v_mov_b32_e32 v0, 0
	s_cselect_b64 s[44:45], -1, 0
	s_cmp_lt_u32 s8, -10
	v_mad_u32_u24 v83, v32, s33, v82
	v_mov_b32_e32 v8, 0
	v_mov_b32_e32 v9, 0
	v_mov_b32_e32 v10, 0
	v_mov_b32_e32 v11, 0
	v_mov_b32_e32 v12, 0
	v_mov_b32_e32 v13, 0
	v_mov_b32_e32 v14, 0
	v_mov_b32_e32 v15, 0
	s_waitcnt lgkmcnt(0)
	s_cselect_b32 s49, 1, 0
	v_lshrrev_b32_e32 v227, 4, v218
	v_and_b32_e32 v244, 15, v218
	v_lshlrev_b32_e32 v244, 4, v244
	v_mul_u32_u24_e32 v245, 0x120, v227
	v_add3_u32 v245, s27, v244, v245
	v_mad_u32_u24 v244, v227, s33, v244
	s_cmp_lg_u32 s72, 0
	s_cbranch_scc1 .Lpf_wait_cnt1
	s_waitcnt vmcnt(0)

.LBB0_1352:
	s_andn2_b64 vcc, exec, s[10:11]
	s_cbranch_vccnz .LBB0_1271
	s_lshl_b32 s8, s74, 12
	v_readlane_b32 s9, v253, 1
	s_or_b32 s12, s8, s9
	v_readlane_b32 s9, v253, 2
	s_lshl_b32 s74, s75, 7
	s_add_i32 s13, s9, s8
	s_and_b32 s8, s74, 0x180
	s_lshl_b32 s28, s8, 1
	v_readlane_b32 s8, v252, 15
	s_add_u32 s8, s8, s28
	v_readlane_b32 s9, v252, 16
	s_addc_u32 s9, s9, 0
	v_readlane_b32 s10, v252, 17
	s_add_u32 s10, s10, s28
	v_readlane_b32 s11, v252, 18
	v_lshlrev_b32_e32 v0, 4, v99
	s_addc_u32 s11, s11, 0
	v_and_b32_e32 v32, 0xf0, v0
	v_ashrrev_i32_e32 v83, 4, v99
	v_lshl_add_u64 v[16:17], s[8:9], 0, v[32:33]
	v_lshl_add_u64 v[18:19], s[10:11], 0, v[32:33]
	s_movk_i32 s8, 0x80
	v_readlane_b32 s10, v253, 3
	v_cmp_gt_i32_e32 vcc, s8, v83
	v_readlane_b32 s11, v253, 4
	v_add_u32_e32 v24, s13, v83
	v_mov_b32_e32 v25, s12
	s_and_b64 vcc, s[10:11], vcc
	v_cndmask_b32_e32 v2, v24, v25, vcc
	v_mad_i64_i32 v[0:1], s[8:9], v2, s70, v[16:17]
	v_mad_i64_i32 v[4:5], s[8:9], v2, s70, v[18:19]
	s_movk_i32 s8, 0x60
	s_nop 0
	v_cmp_gt_i32_e32 vcc, s8, v83
	v_add_u32_e32 v8, 32, v24
	s_and_b64 vcc, s[10:11], vcc
	v_cndmask_b32_e32 v10, v8, v25, vcc
	v_cmp_gt_i32_e32 vcc, 64, v83
	v_add_u32_e32 v20, 64, v24
	s_and_b64 vcc, s[10:11], vcc
	v_cndmask_b32_e32 v22, v20, v25, vcc
	v_mad_i64_i32 v[8:9], s[8:9], v10, s70, v[16:17]
	v_mad_i64_i32 v[12:13], s[8:9], v10, s70, v[18:19]
	v_mad_i64_i32 v[20:21], s[8:9], v22, s70, v[16:17]
	v_cmp_gt_i32_e32 vcc, 32, v83
	s_nop 0
	s_nop 0
	s_nop 0
	v_mad_i64_i32 v[22:23], s[8:9], v22, s70, v[18:19]
	v_add_u32_e32 v20, 0x60, v24
	s_and_b64 vcc, s[10:11], vcc
	v_cndmask_b32_e32 v22, v20, v25, vcc
	v_mad_i64_i32 v[20:21], s[8:9], v22, s70, v[16:17]
	v_cmp_gt_i32_e32 vcc, 0, v83
	v_mad_i64_i32 v[22:23], s[8:9], v22, s70, v[18:19]
	v_add_u32_e32 v20, 0x80, v24
	s_and_b64 vcc, s[10:11], vcc
	v_cndmask_b32_e32 v22, v20, v25, vcc
	v_mad_i64_i32 v[20:21], s[8:9], v22, s70, v[16:17]
	v_mad_i64_i32 v[22:23], s[8:9], v22, s70, v[18:19]
	s_movk_i32 s8, 0xffe0
	s_nop 0
	v_cmp_gt_i32_e32 vcc, s8, v83
	v_add_u32_e32 v20, 0xa0, v24
	s_and_b64 vcc, s[10:11], vcc
	v_cndmask_b32_e32 v22, v20, v25, vcc
	v_mad_i64_i32 v[20:21], s[8:9], v22, s70, v[16:17]
	v_mad_i64_i32 v[22:23], s[8:9], v22, s70, v[18:19]
	s_movk_i32 s8, 0xffc0
	s_nop 0
	v_cmp_gt_i32_e32 vcc, s8, v83
	v_add_u32_e32 v20, 0xc0, v24
	s_and_b64 vcc, s[10:11], vcc
	v_cndmask_b32_e32 v22, v20, v25, vcc
	v_mad_i64_i32 v[20:21], s[8:9], v22, s70, v[16:17]
	v_mad_i64_i32 v[22:23], s[8:9], v22, s70, v[18:19]
	s_movk_i32 s8, 0xffa0
	s_nop 0
	v_cmp_gt_i32_e32 vcc, s8, v83
	v_add_u32_e32 v20, 0xe0, v24
	s_and_b64 vcc, s[10:11], vcc
	v_cndmask_b32_e32 v20, v20, v25, vcc
	v_mad_i64_i32 v[16:17], s[8:9], v20, s70, v[16:17]
	v_mad_i64_i32 v[18:19], s[8:9], v20, s70, v[18:19]
	v_readlane_b32 s8, v252, 27
	s_add_u32 s8, s8, s28
	v_readlane_b32 s9, v252, 28
	v_and_b32_e32 v85, 15, v99
	s_addc_u32 s9, s9, 0
	v_lshl_or_b32 v82, s73, 4, v85
	v_add_u32_e32 v84, s12, v82
	v_mov_b64_e32 v[16:17], s[8:9]
	v_mad_i64_i32 v[16:17], s[8:9], v84, s70, v[16:17]
	v_and_b32_e32 v86, 48, v99
	v_mov_b32_e32 v87, v33
	v_lshl_add_u64 v[28:29], v[16:17], 0, v[86:87]
	s_nop 0
	v_mul_lo_u32 v87, v83, s33
	v_add3_u32 v87, 0, v32, v87
	s_movk_i32 s8, 0x120
	v_mul_lo_u32 v0, v83, s8
	s_add_i32 s8, s73, -2
	v_add3_u32 v0, s27, v32, v0
	v_add_u32_e32 v32, 0, v86
	s_cmp_gt_u32 s8, -11
	v_mov_b32_e32 v0, 0
	s_cselect_b64 s[44:45], -1, 0
	s_cmp_lt_u32 s8, -10
	v_mad_u32_u24 v83, v85, s33, v32
	v_mov_b32_e32 v8, 0
	v_mov_b32_e32 v9, 0
	v_mov_b32_e32 v10, 0
	v_mov_b32_e32 v11, 0
	v_mov_b32_e32 v12, 0
	v_mov_b32_e32 v13, 0
	v_mov_b32_e32 v14, 0
	v_mov_b32_e32 v15, 0
	s_waitcnt lgkmcnt(0)
	s_cselect_b32 s49, 1, 0
	v_lshrrev_b32_e32 v227, 4, v218
	v_and_b32_e32 v244, 15, v218
	v_lshlrev_b32_e32 v244, 4, v244
	v_mul_u32_u24_e32 v245, 0x120, v227
	v_add3_u32 v245, s27, v244, v245
	v_mad_u32_u24 v244, v227, s33, v244
	s_cmp_lg_u32 s72, 0
	s_cbranch_scc1 .Lpf_wait_cnt0
	s_waitcnt vmcnt(0)
